# DF loop off-diagonal tiles: PV split into key halves, exp/pack of keys 32-63 issued between the first half's MFMAs
# baseline (speedup 1.0000x reference)
; #define SBAR() __builtin_amdgcn_sched_barrier(0)
; __device__ __forceinline__ int crow(int r, int hi) { return (r & 3) + 8 * (r >> 2) + 4 * hi; }
; #define PV_RD(S, d0) do { constexpr int b_ = PV_OFF(d0); TRRD(S##l0, b_); TRRD(S##h0, b_ + 2048); TRRD(S##l1, b_ + 4096); TRRD(S##h1, b_ + 6144); TRRD(S##l2, b_ + 8192); TRRD(S##h2, b_ + 10240); TRRD(S##l3, b_ + 12288); TRRD(S##h3, b_ + 14336); } while (0)
; #define PV_W8() do { asm volatile("s_waitcnt lgkmcnt(8)" ::: "memory"); SBAR(); } while (0)
; template <int ND0>
; __device__ __forceinline__ void pv_tile2(f32x16* o, unsigned vb, bf16x8 pa0, bf16x8 pa1, bf16x8 pa2, bf16x8 pa3) {
;     ...
;     s16x4 Al0, Al1, Al2, Al3, Ah0, Ah1, Ah2, Ah3, Bl0, Bl1, Bl2, Bl3, Bh0, Bh1, Bh2, Bh3;
;     PV_RD(A, 0);
;     PV_RD(B, 1); PV_W8(); PV_MM(A, 0); SBAR();
;     PV_RD(A, 2); PV_W8(); PV_MM(B, 1); SBAR();
; template <bool FIXED>
; __device__ __forceinline__ void df_unit(LAS char* lds, bf16_t* QKV, const float* gsub, float lam, float post, int b, int h, int qb, int wave0, float mfix2) {
;     ...
;         if (kb <= qlo + 31) {
;             f32x16 p0, p1; bf16x8 pa0, pa1, pa2, pa3; float alpha;
;             qkt_b<false>(p0, p1, (unsigned)(size_t)(lds + bf * 4 * TILE + mp * TILE), r32, hi, qr);
;             if (kb + 63 > qlo) mask_incl(p0, p1, qm - kb);
;             if constexpr (FIXED) { constexpr float C2f = LOG2E * SCALE; alpha = 1.f;
; #pragma unroll
;                 for (int r = 0; r < 16; ++r) { p0[r] = __builtin_amdgcn_exp2f(fmaf(p0[r], C2f, mfix2)); p1[r] = __builtin_amdgcn_exp2f(fmaf(p1[r], C2f, mfix2)); } }
;             else {
;             partialSM(p0, p1, m_reg, alpha);
;             if (__any(alpha < 1.f)) { if (hi == 0) al_l[r32] = alpha; asm volatile("s_waitcnt lgkmcnt(0)" ::: "memory");
; #pragma unroll
;                 for (int r = 0; r < 16; ++r) { const float a = al_l[crow(r, hi)];
; #pragma unroll
;                     for (int d = 0; d < 8; ++d) o[d][r] *= a; } }
;             }
;             finishSM(p0, p1, alpha, l_reg, pa0, pa1, pa2, pa3);
;             pv_tile2<8>(o, vbase + bf * 4 * TILE + 2 * TILE, pa0, pa1, pa2, pa3);
.LBB0_147:
	s_sub_i32 s1, s19, 63
	s_cmp_gt_u32 s1, s33
	s_cbranch_scc1 .LBB0_144
	s_lshl_b32 s4, s0, 16
	s_add_i32 s0, s34, s4
	v_add_u32_e32 v0, s0, v206
	ds_read_b128 v[130:133], v0 offset:0
	v_add_u32_e32 v210, s0, v207
	ds_read_b128 v[146:149], v210 offset:0
	v_add_u32_e32 v217, s0, v208
	ds_read_b128 v[150:153], v217 offset:0
	v_add_u32_e32 v233, s0, v209
	ds_read_b128 v[154:157], v233 offset:0
	ds_read_b128 v[158:161], v0 offset:0x80
	ds_read_b128 v[218:221], v210 offset:0x80
	ds_read_b128 v[234:237], v217 offset:0x80
	ds_read_b128 v[238:241], v233 offset:0x80
	s_waitcnt lgkmcnt(0)
	v_mfma_f32_32x32x16_bf16 v[130:145], v[130:133], v[162:165], 0
	v_mfma_f32_32x32x16_bf16 v[130:145], v[146:149], v[166:169], v[130:145]
	v_mfma_f32_32x32x16_bf16 v[130:145], v[150:153], v[170:173], v[130:145]
	v_mfma_f32_32x32x16_bf16 v[130:145], v[154:157], v[174:177], v[130:145]
	v_mfma_f32_32x32x16_bf16 v[130:145], v[158:161], v[178:181], v[130:145]
	v_mfma_f32_32x32x16_bf16 v[130:145], v[218:221], v[182:185], v[130:145]
	v_mfma_f32_32x32x16_bf16 v[130:145], v[234:237], v[186:189], v[130:145]
	v_mfma_f32_32x32x16_bf16 v[130:145], v[238:241], v[190:193], v[130:145]
	ds_read_b128 v[146:149], v0 offset:0x2000
	ds_read_b128 v[218:221], v210 offset:0x2000
	ds_read_b128 v[234:237], v217 offset:0x2000
	ds_read_b128 v[238:241], v233 offset:0x2000
	ds_read_b128 v[242:245], v0 offset:0x2080
	ds_read_b128 v[246:249], v210 offset:0x2080
	ds_read_b128 v[210:213], v217 offset:0x2080
	ds_read_b128 v[226:229], v233 offset:0x2080
	s_cmp_le_u32 s19, s15
	s_waitcnt lgkmcnt(0)
	s_cbranch_scc0 .Ldf_diag
	s_nop 0
	v_mfma_f32_32x32x16_bf16 v[146:161], v[146:149], v[162:165], 0
	v_mfma_f32_32x32x16_bf16 v[146:161], v[218:221], v[166:169], v[146:161]
	v_fmamk_f32 v130, v130, 0x3e0293ee, v231
	v_fmamk_f32 v131, v131, 0x3e0293ee, v231
	v_exp_f32_e32 v130, v130
	v_exp_f32_e32 v131, v131
	v_mfma_f32_32x32x16_bf16 v[146:161], v[234:237], v[170:173], v[146:161]
	v_fmamk_f32 v132, v132, 0x3e0293ee, v231
	v_fmamk_f32 v133, v133, 0x3e0293ee, v231
	v_exp_f32_e32 v132, v132
	v_exp_f32_e32 v133, v133
	v_add_f32_e32 v217, 0, v130
	v_add_f32_e32 v217, v131, v217
	v_mfma_f32_32x32x16_bf16 v[146:161], v[238:241], v[174:177], v[146:161]
	v_fmamk_f32 v134, v134, 0x3e0293ee, v231
	v_fmamk_f32 v135, v135, 0x3e0293ee, v231
	v_exp_f32_e32 v134, v134
	v_exp_f32_e32 v135, v135
	v_add_f32_e32 v217, v132, v217
	v_add_f32_e32 v217, v133, v217
	v_mfma_f32_32x32x16_bf16 v[146:161], v[242:245], v[178:181], v[146:161]
	v_fmamk_f32 v136, v136, 0x3e0293ee, v231
	v_fmamk_f32 v137, v137, 0x3e0293ee, v231
	v_exp_f32_e32 v136, v136
	v_exp_f32_e32 v137, v137
	v_add_f32_e32 v217, v134, v217
	v_add_f32_e32 v217, v135, v217
	v_mfma_f32_32x32x16_bf16 v[146:161], v[246:249], v[182:185], v[146:161]
	v_fmamk_f32 v138, v138, 0x3e0293ee, v231
	v_fmamk_f32 v139, v139, 0x3e0293ee, v231
	v_exp_f32_e32 v138, v138
	v_exp_f32_e32 v139, v139
	v_add_f32_e32 v217, v136, v217
	v_add_f32_e32 v217, v137, v217
	v_mfma_f32_32x32x16_bf16 v[146:161], v[210:213], v[186:189], v[146:161]
	v_fmamk_f32 v140, v140, 0x3e0293ee, v231
	v_fmamk_f32 v141, v141, 0x3e0293ee, v231
	v_exp_f32_e32 v140, v140
	v_exp_f32_e32 v141, v141
	v_add_f32_e32 v217, v138, v217
	v_add_f32_e32 v217, v139, v217
	v_mfma_f32_32x32x16_bf16 v[146:161], v[226:229], v[190:193], v[146:161]
	v_fmamk_f32 v142, v142, 0x3e0293ee, v231
	v_fmamk_f32 v143, v143, 0x3e0293ee, v231
	v_exp_f32_e32 v142, v142
	v_exp_f32_e32 v143, v143
	v_add_f32_e32 v217, v140, v217
	v_add_f32_e32 v217, v141, v217
	v_fmamk_f32 v144, v144, 0x3e0293ee, v231
	v_fmamk_f32 v145, v145, 0x3e0293ee, v231
	v_exp_f32_e32 v144, v144
	v_exp_f32_e32 v145, v145
	v_add_f32_e32 v217, v142, v217
	v_add_f32_e32 v217, v143, v217
	v_add_f32_e32 v217, v144, v217
	v_add_f32_e32 v217, v145, v217
	v_cvt_pk_bf16_f32 v130, v130, v131
	v_cvt_pk_bf16_f32 v131, v132, v133
	v_cvt_pk_bf16_f32 v132, v134, v135
	v_cvt_pk_bf16_f32 v133, v136, v137
	v_cvt_pk_bf16_f32 v134, v138, v139
	v_cvt_pk_bf16_f32 v135, v140, v141
	v_cvt_pk_bf16_f32 v136, v142, v143
	v_cvt_pk_bf16_f32 v137, v144, v145
	v_permlane32_swap_b32_e32 v130, v132
	v_permlane32_swap_b32_e32 v131, v133
	v_permlane32_swap_b32_e32 v134, v136
	v_permlane32_swap_b32_e32 v135, v137
	v_add_u32_e32 v0, s4, v214
	ds_read_b64_tr_b16 v[210:211], v0 offset:0
	ds_read_b64_tr_b16 v[212:213], v0 offset:2048
	ds_read_b64_tr_b16 v[218:219], v0 offset:4096
	ds_read_b64_tr_b16 v[220:221], v0 offset:6144
	ds_read_b64_tr_b16 v[226:227], v0 offset:512
	ds_read_b64_tr_b16 v[228:229], v0 offset:2560
	ds_read_b64_tr_b16 v[234:235], v0 offset:4608
	ds_read_b64_tr_b16 v[236:237], v0 offset:6656
	ds_read_b64_tr_b16 v[238:239], v0 offset:1024
	ds_read_b64_tr_b16 v[240:241], v0 offset:3072
	ds_read_b64_tr_b16 v[242:243], v0 offset:5120
	ds_read_b64_tr_b16 v[244:245], v0 offset:7168
	v_fmamk_f32 v146, v146, 0x3e0293ee, v231
	v_fmamk_f32 v147, v147, 0x3e0293ee, v231
	v_exp_f32_e32 v146, v146
	v_exp_f32_e32 v147, v147
	v_fmamk_f32 v148, v148, 0x3e0293ee, v231
	v_fmamk_f32 v149, v149, 0x3e0293ee, v231
	v_exp_f32_e32 v148, v148
	v_exp_f32_e32 v149, v149
	s_waitcnt lgkmcnt(10)
	v_mfma_f32_32x32x16_bf16 v[114:129], v[130:133], v[210:213], v[114:129]
	s_waitcnt lgkmcnt(8)
	v_mfma_f32_32x32x16_bf16 v[114:129], v[134:137], v[218:221], v[114:129]
	v_fmamk_f32 v150, v150, 0x3e0293ee, v231
	v_fmamk_f32 v151, v151, 0x3e0293ee, v231
	v_exp_f32_e32 v150, v150
	v_exp_f32_e32 v151, v151
	v_add_f32_e32 v217, v146, v217
	v_add_f32_e32 v217, v147, v217
	v_add_f32_e32 v217, v148, v217
	v_add_f32_e32 v217, v149, v217
	ds_read_b64_tr_b16 v[210:211], v0 offset:1536
	ds_read_b64_tr_b16 v[212:213], v0 offset:3584
	ds_read_b64_tr_b16 v[218:219], v0 offset:5632
	ds_read_b64_tr_b16 v[220:221], v0 offset:7680
	s_waitcnt lgkmcnt(10)
; #define SBAR() __builtin_amdgcn_sched_barrier(0)
; #define PV_RD(S, d0) do { constexpr int b_ = PV_OFF(d0); TRRD(S##l0, b_); TRRD(S##h0, b_ + 2048); TRRD(S##l1, b_ + 4096); TRRD(S##h1, b_ + 6144); TRRD(S##l2, b_ + 8192); TRRD(S##h2, b_ + 10240); TRRD(S##l3, b_ + 12288); TRRD(S##h3, b_ + 14336); } while (0)
; #define PV_W8() do { asm volatile("s_waitcnt lgkmcnt(8)" ::: "memory"); SBAR(); } while (0)
; #define PV_W0() do { asm volatile("s_waitcnt lgkmcnt(0)" ::: "memory"); SBAR(); } while (0)
; template <int ND0>
; __device__ __forceinline__ void pv_tile2(f32x16* o, unsigned vb, bf16x8 pa0, bf16x8 pa1, bf16x8 pa2, bf16x8 pa3) {
;     ...
;     s16x4 Al0, Al1, Al2, Al3, Ah0, Ah1, Ah2, Ah3, Bl0, Bl1, Bl2, Bl3, Bh0, Bh1, Bh2, Bh3;
;     PV_RD(A, 0);
;     PV_RD(B, 1); PV_W8(); PV_MM(A, 0); SBAR();
;     PV_RD(A, 2); PV_W8(); PV_MM(B, 1); SBAR();
;     if constexpr (ND0 > 4) {
;         PV_RD(B, 3); PV_W8(); PV_MM(A, 2); SBAR();
;         PV_RD(A, 4); PV_W8(); PV_MM(B, 3); SBAR();
;         PV_RD(B, 5); PV_W8(); PV_MM(A, 4); SBAR();
;         PV_RD(A, 6); PV_W8(); PV_MM(B, 5); SBAR();
;         PV_RD(B, 7); PV_W8(); PV_MM(A, 6); SBAR();
;         PV_W0(); PV_MM(B, 7);
; __device__ __forceinline__ void finishSM(f32x16& p0, f32x16& p1, float alpha, float& l_reg, bf16x8& pa0, bf16x8& pa1, bf16x8& pa2, bf16x8& pa3) {
;     ...
;     { auto rr = __builtin_amdgcn_permlane32_swap(__float_as_uint(ps), __float_as_uint(ps), false, false);
;       ps = __uint_as_float(rr[0]) + __uint_as_float(rr[1]); }
;     l_reg = l_reg * alpha + ps;
	v_mfma_f32_32x32x16_bf16 v[98:113], v[130:133], v[226:229], v[98:113]
	s_waitcnt lgkmcnt(8)
	v_mfma_f32_32x32x16_bf16 v[98:113], v[134:137], v[234:237], v[98:113]
	v_fmamk_f32 v152, v152, 0x3e0293ee, v231
	v_fmamk_f32 v153, v153, 0x3e0293ee, v231
	v_exp_f32_e32 v152, v152
	v_exp_f32_e32 v153, v153
	v_add_f32_e32 v217, v150, v217
	v_add_f32_e32 v217, v151, v217
	ds_read_b64_tr_b16 v[226:227], v0 offset:16384
	ds_read_b64_tr_b16 v[228:229], v0 offset:18432
	ds_read_b64_tr_b16 v[234:235], v0 offset:20480
	ds_read_b64_tr_b16 v[236:237], v0 offset:22528
	s_waitcnt lgkmcnt(10)
	v_mfma_f32_32x32x16_bf16 v[82:97], v[130:133], v[238:241], v[82:97]
	s_waitcnt lgkmcnt(8)
	v_mfma_f32_32x32x16_bf16 v[82:97], v[134:137], v[242:245], v[82:97]
	v_fmamk_f32 v154, v154, 0x3e0293ee, v231
	v_fmamk_f32 v155, v155, 0x3e0293ee, v231
	v_exp_f32_e32 v154, v154
	v_exp_f32_e32 v155, v155
	v_add_f32_e32 v217, v152, v217
	v_add_f32_e32 v217, v153, v217
	ds_read_b64_tr_b16 v[238:239], v0 offset:16896
	ds_read_b64_tr_b16 v[240:241], v0 offset:18944
	ds_read_b64_tr_b16 v[242:243], v0 offset:20992
	ds_read_b64_tr_b16 v[244:245], v0 offset:23040
	s_waitcnt lgkmcnt(10)
	v_mfma_f32_32x32x16_bf16 v[66:81], v[130:133], v[210:213], v[66:81]
	s_waitcnt lgkmcnt(8)
	v_mfma_f32_32x32x16_bf16 v[66:81], v[134:137], v[218:221], v[66:81]
	v_fmamk_f32 v156, v156, 0x3e0293ee, v231
	v_fmamk_f32 v157, v157, 0x3e0293ee, v231
	v_exp_f32_e32 v156, v156
	v_exp_f32_e32 v157, v157
	v_add_f32_e32 v217, v154, v217
	v_add_f32_e32 v217, v155, v217
	ds_read_b64_tr_b16 v[210:211], v0 offset:17408
	ds_read_b64_tr_b16 v[212:213], v0 offset:19456
	ds_read_b64_tr_b16 v[218:219], v0 offset:21504
	ds_read_b64_tr_b16 v[220:221], v0 offset:23552
	s_waitcnt lgkmcnt(10)
	v_mfma_f32_32x32x16_bf16 v[50:65], v[130:133], v[226:229], v[50:65]
	s_waitcnt lgkmcnt(8)
	v_mfma_f32_32x32x16_bf16 v[50:65], v[134:137], v[234:237], v[50:65]
	v_fmamk_f32 v158, v158, 0x3e0293ee, v231
	v_fmamk_f32 v159, v159, 0x3e0293ee, v231
	v_exp_f32_e32 v158, v158
	v_exp_f32_e32 v159, v159
	v_add_f32_e32 v217, v156, v217
	v_add_f32_e32 v217, v157, v217
	ds_read_b64_tr_b16 v[226:227], v0 offset:17920
	ds_read_b64_tr_b16 v[228:229], v0 offset:19968
	ds_read_b64_tr_b16 v[234:235], v0 offset:22016
	ds_read_b64_tr_b16 v[236:237], v0 offset:24064
	s_waitcnt lgkmcnt(10)
	v_mfma_f32_32x32x16_bf16 v[34:49], v[130:133], v[238:241], v[34:49]
	s_waitcnt lgkmcnt(8)
	v_mfma_f32_32x32x16_bf16 v[34:49], v[134:137], v[242:245], v[34:49]
	v_fmamk_f32 v160, v160, 0x3e0293ee, v231
	v_fmamk_f32 v161, v161, 0x3e0293ee, v231
	v_exp_f32_e32 v160, v160
	v_exp_f32_e32 v161, v161
	v_add_f32_e32 v217, v158, v217
	v_add_f32_e32 v217, v159, v217
	s_waitcnt lgkmcnt(6)
	v_mfma_f32_32x32x16_bf16 v[18:33], v[130:133], v[210:213], v[18:33]
	s_waitcnt lgkmcnt(4)
	v_mfma_f32_32x32x16_bf16 v[18:33], v[134:137], v[218:221], v[18:33]
	v_add_f32_e32 v217, v160, v217
	v_add_f32_e32 v217, v161, v217
	v_cvt_pk_bf16_f32 v138, v146, v147
	v_cvt_pk_bf16_f32 v139, v148, v149
	v_cvt_pk_bf16_f32 v140, v150, v151
	v_cvt_pk_bf16_f32 v141, v152, v153
	s_waitcnt lgkmcnt(2)
	v_mfma_f32_32x32x16_bf16 v[2:17], v[130:133], v[226:229], v[2:17]
	s_waitcnt lgkmcnt(0)
	v_mfma_f32_32x32x16_bf16 v[2:17], v[134:137], v[234:237], v[2:17]
	v_cvt_pk_bf16_f32 v142, v154, v155
	v_cvt_pk_bf16_f32 v143, v156, v157
	v_cvt_pk_bf16_f32 v144, v158, v159
	v_cvt_pk_bf16_f32 v145, v160, v161
	v_mov_b32_e32 v246, v217
	v_permlane32_swap_b32_e32 v138, v140
	v_permlane32_swap_b32_e32 v139, v141
	v_permlane32_swap_b32_e32 v142, v144
	v_permlane32_swap_b32_e32 v143, v145
	v_permlane32_swap_b32_e32 v217, v246
	ds_read_b64_tr_b16 v[146:147], v0 offset:8192
	ds_read_b64_tr_b16 v[148:149], v0 offset:10240
	ds_read_b64_tr_b16 v[150:151], v0 offset:12288
	ds_read_b64_tr_b16 v[152:153], v0 offset:14336
	ds_read_b64_tr_b16 v[154:155], v0 offset:8704
	ds_read_b64_tr_b16 v[156:157], v0 offset:10752
	ds_read_b64_tr_b16 v[158:159], v0 offset:12800
	ds_read_b64_tr_b16 v[160:161], v0 offset:14848
	ds_read_b64_tr_b16 v[238:239], v0 offset:9216
	ds_read_b64_tr_b16 v[240:241], v0 offset:11264
	ds_read_b64_tr_b16 v[242:243], v0 offset:13312
	ds_read_b64_tr_b16 v[244:245], v0 offset:15360
	v_add_f32_e32 v217, v217, v246
	v_add_f32_e32 v216, v216, v217
	s_waitcnt lgkmcnt(10)
	v_mfma_f32_32x32x16_bf16 v[114:129], v[138:141], v[146:149], v[114:129]
	s_waitcnt lgkmcnt(8)
	v_mfma_f32_32x32x16_bf16 v[114:129], v[142:145], v[150:153], v[114:129]
	ds_read_b64_tr_b16 v[210:211], v0 offset:9728
	ds_read_b64_tr_b16 v[212:213], v0 offset:11776
	ds_read_b64_tr_b16 v[218:219], v0 offset:13824
	ds_read_b64_tr_b16 v[220:221], v0 offset:15872
	s_waitcnt lgkmcnt(10)
	v_mfma_f32_32x32x16_bf16 v[98:113], v[138:141], v[154:157], v[98:113]
	s_waitcnt lgkmcnt(8)
	v_mfma_f32_32x32x16_bf16 v[98:113], v[142:145], v[158:161], v[98:113]
	ds_read_b64_tr_b16 v[226:227], v0 offset:24576
	ds_read_b64_tr_b16 v[228:229], v0 offset:26624
	ds_read_b64_tr_b16 v[234:235], v0 offset:28672
	ds_read_b64_tr_b16 v[236:237], v0 offset:30720
	s_waitcnt lgkmcnt(10)
	v_mfma_f32_32x32x16_bf16 v[82:97], v[138:141], v[238:241], v[82:97]
	s_waitcnt lgkmcnt(8)
	v_mfma_f32_32x32x16_bf16 v[82:97], v[142:145], v[242:245], v[82:97]
	ds_read_b64_tr_b16 v[146:147], v0 offset:25088
	ds_read_b64_tr_b16 v[148:149], v0 offset:27136
	ds_read_b64_tr_b16 v[150:151], v0 offset:29184
	ds_read_b64_tr_b16 v[152:153], v0 offset:31232
	s_waitcnt lgkmcnt(10)
	v_mfma_f32_32x32x16_bf16 v[66:81], v[138:141], v[210:213], v[66:81]
	s_waitcnt lgkmcnt(8)
	v_mfma_f32_32x32x16_bf16 v[66:81], v[142:145], v[218:221], v[66:81]
	ds_read_b64_tr_b16 v[154:155], v0 offset:25600
	ds_read_b64_tr_b16 v[156:157], v0 offset:27648
	ds_read_b64_tr_b16 v[158:159], v0 offset:29696
	ds_read_b64_tr_b16 v[160:161], v0 offset:31744
	s_waitcnt lgkmcnt(10)
	v_mfma_f32_32x32x16_bf16 v[50:65], v[138:141], v[226:229], v[50:65]
	s_waitcnt lgkmcnt(8)
	v_mfma_f32_32x32x16_bf16 v[50:65], v[142:145], v[234:237], v[50:65]
	ds_read_b64_tr_b16 v[238:239], v0 offset:26112
	ds_read_b64_tr_b16 v[240:241], v0 offset:28160
	ds_read_b64_tr_b16 v[242:243], v0 offset:30208
	ds_read_b64_tr_b16 v[244:245], v0 offset:32256
	s_waitcnt lgkmcnt(10)
	v_mfma_f32_32x32x16_bf16 v[34:49], v[138:141], v[146:149], v[34:49]
	s_waitcnt lgkmcnt(8)
	v_mfma_f32_32x32x16_bf16 v[34:49], v[142:145], v[150:153], v[34:49]
	s_waitcnt lgkmcnt(6)
	v_mfma_f32_32x32x16_bf16 v[18:33], v[138:141], v[154:157], v[18:33]
	s_waitcnt lgkmcnt(4)
	v_mfma_f32_32x32x16_bf16 v[18:33], v[142:145], v[158:161], v[18:33]
	s_waitcnt lgkmcnt(2)
	v_mfma_f32_32x32x16_bf16 v[2:17], v[138:141], v[238:241], v[2:17]
	s_waitcnt lgkmcnt(0)
	v_mfma_f32_32x32x16_bf16 v[2:17], v[142:145], v[242:245], v[2:17]
	s_branch .LBB0_144
